# attention softmax: dead ds_bpermute index computations removed (9 VALU per chunk)
# speedup vs baseline: 1.0022x; 1.0022x over previous
.Lmask_join:
	v_max3_f32 v81, v82, v114, v2
	v_or_b32_e32 v82, s67, v103
	v_cmp_lt_i32_e32 vcc, s68, v82
	s_or_b64 s[16:17], s[0:1], vcc
	v_cmp_le_i32_e32 vcc, v82, v44
	s_and_b64 vcc, s[16:17], vcc
	v_or_b32_e32 v116, v103, v116
	v_cndmask_b32_e32 v108, v96, v40, vcc
	v_cmp_lt_i32_e32 vcc, s69, v82
	s_or_b64 s[16:17], s[0:1], vcc
	v_cmp_lt_i32_e32 vcc, v82, v44
	s_and_b64 vcc, s[16:17], vcc
	v_mul_u32_u24_e32 v116, 0x90, v116
	v_cndmask_b32_e32 v109, v96, v41, vcc
	v_or_b32_e32 v41, 2, v82
	v_cmp_lt_i32_e32 vcc, s68, v41
	s_or_b64 s[16:17], s[0:1], vcc
	v_cmp_le_i32_e32 vcc, v41, v44
	s_and_b64 vcc, s[16:17], vcc
	v_or_b32_e32 v41, 3, v82
	v_cndmask_b32_e32 v110, v96, v42, vcc
	v_cmp_lt_i32_e32 vcc, s68, v41
	s_or_b64 s[0:1], s[0:1], vcc
	v_cmp_le_i32_e32 vcc, v41, v44

	s_and_b64 vcc, s[0:1], vcc
	v_xor_b32_e32 v41, 16, v95

	v_cndmask_b32_e32 v111, v96, v43, vcc

	v_max3_f32 v40, v81, v108, v109
	v_max3_f32 v40, v40, v110, v111


	v_mov_b32_e32 v41, v40
	s_nop 1
	v_permlane16_swap_b32_e32 v40, v41
	s_or_b32 s0, s14, s50
	v_add3_u32 v104, 0, v116, v104
	s_mulk_i32 s13, 0x90
	s_mulk_i32 s0, 0x90
	s_waitcnt lgkmcnt(0)
	v_max_f32_e32 v41, v41, v41
	v_max_f32_e32 v40, v40, v41


	s_mulk_i32 s11, 0x90
	s_mulk_i32 s9, 0x90


	v_mov_b32_e32 v41, v40
	s_nop 1
	v_permlane32_swap_b32_e32 v40, v41
	s_mulk_i32 s7, 0x90
	s_mulk_i32 s6, 0x90
	s_waitcnt lgkmcnt(0)
	v_max_f32_e32 v41, v41, v41
	v_max_f32_e32 v40, v40, v41
	v_mul_f32_e32 v40, 0x3e38aa3b, v40
	v_max_f32_e32 v41, v53, v53
	v_max_f32_e32 v107, v40, v41
	v_fma_f32 v42, v74, s70, -v107
	v_fma_f32 v1, v1, s70, -v107
	v_exp_f32_e32 v82, v42
	v_fma_f32 v42, v75, s70, -v107
	v_exp_f32_e32 v88, v1
	v_fma_f32 v1, v47, s70, -v107
	v_exp_f32_e32 v83, v42
	v_fma_f32 v42, v76, s70, -v107
	v_exp_f32_e32 v89, v1
	v_exp_f32_e32 v84, v42
	v_fma_f32 v42, v46, s70, -v107
	v_fma_f32 v43, v80, s70, -v107
	v_exp_f32_e32 v85, v42
	v_exp_f32_e32 v80, v43
	v_fma_f32 v43, v77, s70, -v107
	v_exp_f32_e32 v81, v43
	v_fma_f32 v0, v0, s70, -v107
	v_exp_f32_e32 v87, v0
	v_pk_add_f32 v[0:1], v[88:89], 0 op_sel_hi:[1,0]
	v_fma_f32 v42, v78, s70, -v107
	v_exp_f32_e32 v74, v42
	v_fma_f32 v42, v79, s70, -v107
	v_pk_add_f32 v[0:1], v[84:85], v[0:1]
	v_exp_f32_e32 v75, v42
	v_pk_add_f32 v[42:43], v[80:81], v[0:1]
	v_fma_f32 v0, v90, s70, -v107
	v_exp_f32_e32 v76, v0
	v_fma_f32 v0, v91, s70, -v107
	v_exp_f32_e32 v77, v0
	v_fma_f32 v0, v122, s70, -v107
	v_exp_f32_e32 v78, v0
	v_fma_f32 v0, v123, s70, -v107
	v_fma_f32 v40, v45, s70, -v107
	v_exp_f32_e32 v79, v0
	v_fma_f32 v44, v126, s70, -v107
	v_fma_f32 v45, v127, s70, -v107
	v_exp_f32_e32 v44, v44
	v_exp_f32_e32 v45, v45
	v_exp_f32_e32 v86, v40
	v_pk_add_f32 v[42:43], v[78:79], v[42:43]
	v_fma_f32 v0, v124, s70, -v107
	v_fma_f32 v1, v125, s70, -v107
	v_pk_add_f32 v[46:47], v[44:45], v[42:43]
	v_fma_f32 v42, v130, s70, -v107
	v_add_u32_e32 v126, s13, v104
	v_add_u32_e32 v130, s0, v104
	v_pk_add_f32 v[40:41], v[86:87], 0 op_sel_hi:[1,0]
	v_exp_f32_e32 v0, v0
	v_exp_f32_e32 v1, v1
	ds_read_b64_tr_b16 v[116:117], v126 offset:36864
	ds_read_b64_tr_b16 v[118:119], v130 offset:36864
	v_pk_add_f32 v[40:41], v[82:83], v[40:41]
	v_fma_f32 v43, v131, s70, -v107
	v_pk_add_f32 v[40:41], v[74:75], v[40:41]
	s_or_b32 s0, s12, s51
	v_pk_add_f32 v[40:41], v[76:77], v[40:41]
	s_mulk_i32 s0, 0x90
	v_pk_add_f32 v[90:91], v[0:1], v[40:41]
	v_fma_f32 v40, v128, s70, -v107
	v_fma_f32 v41, v129, s70, -v107
	ds_read_b64_tr_b16 v[122:123], v130 offset:36896
	ds_read_b64_tr_b16 v[120:121], v126 offset:36896
	ds_read_b64_tr_b16 v[124:125], v126 offset:36928
	ds_read_b64_tr_b16 v[128:129], v126 offset:36960
	ds_read_b64_tr_b16 v[126:127], v130 offset:36928
	ds_read_b64_tr_b16 v[130:131], v130 offset:36960
	v_cvt_pk_bf16_f32 v86, v86, v87
	v_cvt_pk_bf16_f32 v87, v88, v89
	v_cvt_pk_bf16_f32 v88, v82, v83
	v_cvt_pk_bf16_f32 v89, v84, v85
	v_fma_f32 v83, v115, s70, -v107
	v_add_u32_e32 v115, s11, v104
	v_add_u32_e32 v138, s0, v104
	s_waitcnt lgkmcnt(6)
	v_mfma_f32_16x16x32_bf16 v[116:119], v[116:119], v[86:89], 0
	v_fma_f32 v82, v132, s70, -v107
	v_fma_f32 v84, v133, s70, -v107
	v_fma_f32 v85, v134, s70, -v107
	s_waitcnt lgkmcnt(4)
	v_mfma_f32_16x16x32_bf16 v[120:123], v[120:123], v[86:89], 0
	v_cvt_pk_bf16_f32 v74, v74, v75
	v_cvt_pk_bf16_f32 v75, v80, v81
	v_cvt_pk_bf16_f32 v76, v76, v77
	s_waitcnt lgkmcnt(1)
	v_mfma_f32_16x16x32_bf16 v[124:127], v[124:127], v[86:89], 0
	v_cvt_pk_bf16_f32 v77, v78, v79
	v_fma_f32 v112, v112, s70, -v107
	s_or_b32 s0, s10, s33
	s_waitcnt lgkmcnt(0)
	v_mfma_f32_16x16x32_bf16 v[86:89], v[128:131], v[86:89], 0
	ds_read_b64_tr_b16 v[128:129], v115 offset:36864
	ds_read_b64_tr_b16 v[130:131], v138 offset:36864
	ds_read_b64_tr_b16 v[80:81], v138 offset:36896
	ds_read_b64_tr_b16 v[78:79], v115 offset:36896
	ds_read_b64_tr_b16 v[132:133], v115 offset:36928
	ds_read_b64_tr_b16 v[136:137], v115 offset:36960
	ds_read_b64_tr_b16 v[134:135], v138 offset:36928
	ds_read_b64_tr_b16 v[138:139], v138 offset:36960
	v_exp_f32_e32 v140, v112
	v_fma_f32 v112, v113, s70, -v107
	s_mulk_i32 s0, 0x90
	s_waitcnt lgkmcnt(6)
	v_mfma_f32_16x16x32_bf16 v[116:119], v[128:131], v[74:77], v[116:119]
	v_exp_f32_e32 v141, v112
	v_fma_f32 v112, v114, s70, -v107
	v_exp_f32_e32 v40, v40
	s_waitcnt lgkmcnt(4)
	v_mfma_f32_16x16x32_bf16 v[78:81], v[78:81], v[74:77], v[120:123]
	v_exp_f32_e32 v41, v41
	v_exp_f32_e32 v42, v42
	v_exp_f32_e32 v43, v43
	s_waitcnt lgkmcnt(1)
	v_mfma_f32_16x16x32_bf16 v[120:123], v[132:135], v[74:77], v[124:127]
	v_exp_f32_e32 v132, v112
	v_exp_f32_e32 v82, v82
	v_exp_f32_e32 v83, v83
	s_waitcnt lgkmcnt(0)
	v_mfma_f32_16x16x32_bf16 v[74:77], v[136:139], v[74:77], v[86:89]
	v_add_f32_e64 v90, v40, v90
	v_add_f32_e64 v91, v41, v91
	v_pk_add_f32 v[46:47], v[42:43], v[46:47]
	v_exp_f32_e32 v84, v84
	v_cvt_pk_bf16_f32 v86, v0, v1
	v_add_u32_e32 v0, s9, v104
	v_add_u32_e32 v1, s0, v104
	ds_read_b64_tr_b16 v[112:113], v0 offset:36864
	ds_read_b64_tr_b16 v[114:115], v1 offset:36864
	v_cvt_pk_bf16_f32 v88, v40, v41
	v_cvt_pk_bf16_f32 v89, v42, v43
	ds_read_b64_tr_b16 v[42:43], v1 offset:36896
	ds_read_b64_tr_b16 v[40:41], v0 offset:36896
	ds_read_b64_tr_b16 v[124:125], v0 offset:36928
	ds_read_b64_tr_b16 v[128:129], v0 offset:36960
	ds_read_b64_tr_b16 v[126:127], v1 offset:36928
	ds_read_b64_tr_b16 v[130:131], v1 offset:36960
	s_or_b32 s0, s8, s35
	v_exp_f32_e32 v85, v85
	v_pk_add_f32 v[90:91], v[82:83], v[90:91]
	v_cvt_pk_bf16_f32 v87, v44, v45
	v_fma_f32 v0, v2, s70, -v107
	v_fma_f32 v2, v108, s70, -v107
	v_fma_f32 v44, v110, s70, -v107
	s_mulk_i32 s0, 0x90
	v_exp_f32_e32 v133, v0
	v_pk_add_f32 v[0:1], v[140:141], v[90:91]
	s_waitcnt lgkmcnt(4)
	v_mfma_f32_16x16x32_bf16 v[40:43], v[40:43], v[86:89], v[78:81]
	v_exp_f32_e32 v90, v2
	v_fma_f32 v2, v109, s70, -v107
	v_add_u32_e32 v45, s7, v104
	s_waitcnt lgkmcnt(1)
	v_mfma_f32_16x16x32_bf16 v[78:81], v[124:127], v[86:89], v[120:123]
	v_exp_f32_e32 v124, v44
	v_fma_f32 v44, v111, s70, -v107
	v_add_u32_e32 v91, s0, v104
	v_mfma_f32_16x16x32_bf16 v[112:115], v[112:115], v[86:89], v[116:119]
	v_exp_f32_e32 v125, v44
	v_pk_add_f32 v[46:47], v[84:85], v[46:47]
	s_and_b64 s[0:1], s[52:53], exec
	s_waitcnt lgkmcnt(0)
	v_mfma_f32_16x16x32_bf16 v[74:77], v[128:131], v[86:89], v[74:77]
	ds_read_b64_tr_b16 v[86:87], v45 offset:36864
	ds_read_b64_tr_b16 v[88:89], v91 offset:36864
	ds_read_b64_tr_b16 v[110:111], v91 offset:36896
	ds_read_b64_tr_b16 v[108:109], v45 offset:36896
	ds_read_b64_tr_b16 v[116:117], v45 offset:36928
	ds_read_b64_tr_b16 v[120:121], v45 offset:36960
	ds_read_b64_tr_b16 v[118:119], v91 offset:36928
	ds_read_b64_tr_b16 v[122:123], v91 offset:36960
	v_exp_f32_e32 v91, v2
	v_cvt_pk_bf16_f32 v82, v82, v83
	v_cvt_pk_bf16_f32 v83, v84, v85
	v_cvt_pk_bf16_f32 v84, v140, v141
	v_cvt_pk_bf16_f32 v85, v132, v133
	v_pk_add_f32 v[44:45], v[132:133], v[46:47]
	s_cselect_b32 s0, s96, s41
	s_waitcnt lgkmcnt(4)
	v_mfma_f32_16x16x32_bf16 v[40:43], v[108:111], v[82:85], v[40:43]
	v_add_f32_e64 v108, v124, v44
	v_add_f32_e64 v109, v125, v45
	v_pk_add_f32 v[0:1], v[90:91], v[0:1]
	s_lshl_b32 s0, s0, 7
	v_pk_mov_b32 v[110:111], v[0:1], v[108:109] op_sel:[1,0]
	v_mov_b32_e32 v1, v109
	s_or_b32 s0, s0, s75
	v_pk_add_f32 v[0:1], v[110:111], v[0:1]
	s_mulk_i32 s0, 0x90
	s_waitcnt lgkmcnt(1)
	v_mfma_f32_16x16x32_bf16 v[44:47], v[116:119], v[82:85], v[78:81]
	v_add_f32_e32 v116, v0, v1
	v_cvt_pk_bf16_f32 v0, v90, v91
	v_add_u32_e32 v90, s6, v104
	v_add_u32_e32 v91, s0, v104
	ds_read_b64_tr_b16 v[78:79], v90 offset:36864
	ds_read_b64_tr_b16 v[80:81], v91 offset:36864
	v_mfma_f32_16x16x32_bf16 v[86:89], v[86:89], v[82:85], v[112:115]
	v_cvt_pk_bf16_f32 v1, v124, v125
	v_mov_b32_e32 v2, v3
	s_waitcnt vmcnt(0)
	v_permlane16_swap_b32_e32 v238, v240
	v_permlane16_swap_b32_e32 v239, v241
	v_permlane16_swap_b32_e32 v242, v244
	v_permlane16_swap_b32_e32 v243, v245
	v_permlane16_swap_b32_e32 v246, v248
	v_permlane16_swap_b32_e32 v247, v249
	v_permlane16_swap_b32_e32 v250, v252
	v_permlane16_swap_b32_e32 v251, v253
	v_permlane16_swap_b32_e32 v154, v156
	v_permlane16_swap_b32_e32 v155, v157
	v_permlane16_swap_b32_e32 v216, v218
	v_permlane16_swap_b32_e32 v217, v219
	v_mov_b64_e32 v[68:69], v[238:239]
	v_mov_b64_e32 v[62:63], v[240:241]
	v_mov_b64_e32 v[56:57], v[242:243]
	v_mov_b64_e32 v[48:49], v[244:245]
	v_mov_b64_e32 v[70:71], v[246:247]
	v_mov_b64_e32 v[64:65], v[248:249]
	v_mov_b64_e32 v[58:59], v[250:251]
	v_mov_b64_e32 v[50:51], v[252:253]
	v_mov_b64_e32 v[72:73], v[154:155]
	v_mov_b64_e32 v[66:67], v[156:157]
	v_mov_b64_e32 v[60:61], v[216:217]
	v_mov_b64_e32 v[54:55], v[218:219]
	v_and_b32_e32 v104, 0xffff0000, v70
	s_waitcnt lgkmcnt(2)
	v_mfma_f32_16x16x32_bf16 v[74:77], v[120:123], v[82:85], v[74:77]
	ds_read_b64_tr_b16 v[84:85], v91 offset:36896
	ds_read_b64_tr_b16 v[82:83], v90 offset:36896
	ds_read_b64_tr_b16 v[108:109], v90 offset:36928
	ds_read_b64_tr_b16 v[112:113], v90 offset:36960
	ds_read_b64_tr_b16 v[110:111], v91 offset:36928
	ds_read_b64_tr_b16 v[114:115], v91 offset:36960
	v_lshlrev_b32_e32 v90, 16, v70
	v_mul_f32_e32 v90, 0xbfb8aa3b, v90
	s_waitcnt lgkmcnt(6)
	v_mfma_f32_16x16x32_bf16 v[78:81], v[78:81], v[0:3], v[86:89]
	v_exp_f32_e32 v90, v90
	s_add_i32 s40, s40, 1
	s_nop 0
	v_mov_b32_e32 v158, v116
	s_nop 1
	v_permlane16_swap_b32_e32 v116, v158
	s_waitcnt lgkmcnt(4)
	v_mfma_f32_16x16x32_bf16 v[82:85], v[82:85], v[0:3], v[40:43]
	v_lshlrev_b32_e32 v88, 16, v73
	v_and_b32_e32 v89, 0xffff0000, v73
	v_lshlrev_b32_e32 v105, 16, v71
	s_waitcnt lgkmcnt(0)
	v_add_f32_e32 v40, v116, v158
	v_mov_b32_e32 v41, v40
	s_nop 1
	v_permlane32_swap_b32_e32 v40, v41
	v_sub_f32_e32 v42, v53, v107
	v_exp_f32_e32 v42, v42
	v_mfma_f32_16x16x32_bf16 v[44:47], v[108:111], v[0:3], v[44:47]
	v_and_b32_e32 v106, 0xffff0000, v69
	s_waitcnt lgkmcnt(0)
	v_add_f32_e32 v40, v40, v41
	v_add_f32_e32 v86, v42, v40
	v_mfma_f32_16x16x32_bf16 v[40:43], v[112:115], v[0:3], v[74:77]
	v_lshl_add_u32 v1, v103, 2, v102
	v_lshlrev_b32_e32 v2, 16, v68
	v_lshlrev_b32_e32 v102, 16, v69
	v_add_u32_e32 v74, s38, v101
	s_mov_b32 s100, 0x9f57000
	v_lshl_add_u64 v[22:23], v[20:21], 0, s[100:101]
	global_load_dwordx4 v[28:31], v[22:23], off offset:3072
	v_and_b32_e32 v101, 0xffff0000, v68
	v_lshlrev_b32_e32 v68, 16, v72
	v_and_b32_e32 v69, 0xffff0000, v72
	v_pk_mul_f32 v[72:73], v[68:69], v[68:69]
	v_mul_f32_e32 v2, 0xbfb8aa3b, v2
	v_fmamk_f32 v72, v72, 0xbdd2d3e7, v93
	v_mul_f32_e32 v72, v72, v68
	v_exp_f32_e32 v2, v2
	v_exp_f32_e32 v91, v72
	v_mul_f32_e32 v72, 0xbfb8aa3b, v101
	v_fmamk_f32 v73, v73, 0xbdd2d3e7, v93
	v_and_b32_e32 v107, 0xffff0000, v71
	v_pk_mul_f32 v[70:71], v[88:89], v[88:89]
	v_exp_f32_e32 v101, v72
	v_mul_f32_e32 v72, 0xbfb8aa3b, v104
	v_mul_f32_e32 v73, v73, v69
	v_exp_f32_e32 v72, v72
	v_exp_f32_e32 v73, v73
	v_fmamk_f32 v70, v70, 0xbdd2d3e7, v93
	v_mul_f32_e32 v102, 0xbfb8aa3b, v102
	v_mul_f32_e32 v104, 0xbfb8aa3b, v105
	v_mul_f32_e32 v70, v70, v88
	v_exp_f32_e32 v102, v102
	v_exp_f32_e32 v104, v104
	v_exp_f32_e32 v105, v70
	v_mul_f32_e32 v70, 0xbfb8aa3b, v106
	v_fmamk_f32 v71, v71, 0xbdd2d3e7, v93
	v_add_f32_e32 v2, 1.0, v2
	v_pk_add_f32 v[90:91], v[90:91], 1.0 op_sel_hi:[1,0]
	v_exp_f32_e32 v109, v70
	v_mul_f32_e32 v70, 0xbfb8aa3b, v107
	v_mul_f32_e32 v71, v71, v89
	v_rcp_f32_e32 v106, v2
	v_mul_f32_e32 v2, v90, v91
	v_exp_f32_e32 v70, v70
	v_exp_f32_e32 v71, v71
	v_rcp_f32_e32 v90, v2
	v_add_f32_e32 v2, 1.0, v101
	v_pk_add_f32 v[72:73], v[72:73], 1.0 op_sel_hi:[1,0]
	v_rcp_f32_e32 v107, v2
	v_mul_f32_e32 v2, v72, v73
	v_ashrrev_i32_e32 v75, 31, v74
	v_rcp_f32_e32 v91, v2
	v_add_f32_e32 v2, 1.0, v102
	v_pk_add_f32 v[72:73], v[104:105], 1.0 op_sel_hi:[1,0]
	v_lshlrev_b64 v[74:75], 11, v[74:75]
	v_rcp_f32_e32 v108, v2
	v_mul_f32_e32 v2, v72, v73
	v_rcp_f32_e32 v0, v86
	v_lshl_add_u64 v[86:87], s[44:45], 0, v[74:75]
	ds_read_b128 v[74:77], v1
	v_rcp_f32_e32 v104, v2
	v_add_f32_e32 v2, 1.0, v109
	v_pk_add_f32 v[70:71], v[70:71], 1.0 op_sel_hi:[1,0]
	v_rcp_f32_e32 v109, v2
	v_mul_f32_e32 v2, v70, v71
	v_rcp_f32_e32 v105, v2
	ds_read_b128 v[70:73], v1 offset:64
	s_waitcnt lgkmcnt(1)
	v_pk_mul_f32 v[76:77], v[76:77], v[88:89]
	v_pk_mul_f32 v[68:69], v[74:75], v[68:69]
	v_pk_mul_f32 v[80:81], v[0:1], v[80:81] op_sel_hi:[0,1]
	v_pk_mul_f32 v[78:79], v[0:1], v[78:79] op_sel_hi:[0,1]
	v_pk_mul_f32 v[68:69], v[90:91], v[68:69]
	v_pk_mul_f32 v[74:75], v[104:105], v[76:77]
	v_pk_fma_f32 v[68:69], v[106:107], v[78:79], v[68:69]
	v_pk_fma_f32 v[74:75], v[108:109], v[80:81], v[74:75]
	v_lshlrev_b32_e32 v2, 1, v103
	v_cvt_pk_bf16_f32 v76, v68, v69
	v_cvt_pk_bf16_f32 v77, v74, v75
	v_lshl_add_u64 v[68:69], v[86:87], 0, v[2:3]
	v_bfe_u32 v158, v52, 4, 1
	v_mul_u32_u24_e32 v158, 24, v158
	v_mov_b32_e32 v159, 0
	v_lshl_add_u64 v[158:159], v[68:69], 0, v[158:159]
	v_mov_b64_e32 v[238:239], v[76:77]
	v_pk_mul_f32 v[74:75], v[0:1], v[84:85] op_sel_hi:[0,1]
	v_pk_mul_f32 v[76:77], v[0:1], v[82:83] op_sel_hi:[0,1]
	v_lshlrev_b32_e32 v2, 16, v62
	v_and_b32_e32 v82, 0xffff0000, v62
	v_lshlrev_b32_e32 v83, 16, v63
	v_and_b32_e32 v84, 0xffff0000, v63
	v_lshlrev_b32_e32 v62, 16, v66
	v_and_b32_e32 v63, 0xffff0000, v66
	v_pk_mul_f32 v[78:79], v[62:63], v[62:63]
	v_lshlrev_b32_e32 v80, 16, v64
	v_fmamk_f32 v78, v78, 0xbdd2d3e7, v93
	v_mul_f32_e32 v2, 0xbfb8aa3b, v2
	v_mul_f32_e32 v80, 0xbfb8aa3b, v80
	v_mul_f32_e32 v78, v78, v62
	v_and_b32_e32 v85, 0xffff0000, v64
	v_lshlrev_b32_e32 v86, 16, v65
	v_and_b32_e32 v87, 0xffff0000, v65
	s_mov_b32 s100, 0x9f5a000
	v_lshl_add_u64 v[24:25], v[20:21], 0, s[100:101]
	global_load_dwordx4 v[24:27], v[24:25], off offset:2048
	v_lshlrev_b32_e32 v64, 16, v67
	v_and_b32_e32 v65, 0xffff0000, v67
	v_exp_f32_e32 v2, v2
	v_exp_f32_e32 v80, v80
	v_exp_f32_e32 v81, v78
	v_mul_f32_e32 v78, 0xbfb8aa3b, v82
	v_fmamk_f32 v79, v79, 0xbdd2d3e7, v93
	v_pk_mul_f32 v[66:67], v[64:65], v[64:65]
	v_exp_f32_e32 v88, v78
	v_mul_f32_e32 v78, 0xbfb8aa3b, v85
	v_mul_f32_e32 v79, v79, v63
	v_exp_f32_e32 v78, v78
	v_exp_f32_e32 v79, v79
	v_mul_f32_e32 v82, 0xbfb8aa3b, v83
	v_fmamk_f32 v66, v66, 0xbdd2d3e7, v93
	v_exp_f32_e32 v89, v82
	v_mul_f32_e32 v82, 0xbfb8aa3b, v86
	v_mul_f32_e32 v66, v66, v64
	v_exp_f32_e32 v82, v82
	v_exp_f32_e32 v83, v66
	v_mul_f32_e32 v66, 0xbfb8aa3b, v84
	v_fmamk_f32 v67, v67, 0xbdd2d3e7, v93
	v_add_f32_e32 v2, 1.0, v2
	v_pk_add_f32 v[80:81], v[80:81], 1.0 op_sel_hi:[1,0]
	v_exp_f32_e32 v86, v66
	v_mul_f32_e32 v66, 0xbfb8aa3b, v87
	v_mul_f32_e32 v67, v67, v65
	v_rcp_f32_e32 v84, v2
	v_mul_f32_e32 v2, v80, v81
	v_exp_f32_e32 v66, v66
	v_exp_f32_e32 v67, v67
	v_rcp_f32_e32 v80, v2
	v_add_f32_e32 v2, 1.0, v88
	v_pk_add_f32 v[78:79], v[78:79], 1.0 op_sel_hi:[1,0]
	v_rcp_f32_e32 v85, v2
	v_mul_f32_e32 v2, v78, v79
	v_rcp_f32_e32 v81, v2
	v_add_f32_e32 v2, 1.0, v89
	v_pk_add_f32 v[82:83], v[82:83], 1.0 op_sel_hi:[1,0]
	v_rcp_f32_e32 v78, v2
	v_mul_f32_e32 v2, v82, v83
	v_rcp_f32_e32 v82, v2
	v_add_f32_e32 v2, 1.0, v86
	v_pk_add_f32 v[66:67], v[66:67], 1.0 op_sel_hi:[1,0]
	v_rcp_f32_e32 v79, v2
	v_mul_f32_e32 v2, v66, v67
	v_rcp_f32_e32 v83, v2
	s_waitcnt lgkmcnt(0)
	v_pk_mul_f32 v[64:65], v[72:73], v[64:65]
	v_lshlrev_b32_e32 v2, 16, v56
	v_and_b32_e32 v72, 0xffff0000, v56
	v_pk_mul_f32 v[64:65], v[82:83], v[64:65]
	v_lshlrev_b32_e32 v73, 16, v57
	v_pk_fma_f32 v[64:65], v[78:79], v[74:75], v[64:65]
	v_and_b32_e32 v74, 0xffff0000, v57
	v_lshlrev_b32_e32 v56, 16, v60
	v_and_b32_e32 v57, 0xffff0000, v60
	v_pk_mul_f32 v[66:67], v[0:1], v[46:47] op_sel_hi:[0,1]
	v_pk_mul_f32 v[46:47], v[56:57], v[56:57]
	v_pk_mul_f32 v[62:63], v[70:71], v[62:63]
	v_lshlrev_b32_e32 v75, 16, v58
	v_fmamk_f32 v46, v46, 0xbdd2d3e7, v93
	v_pk_mul_f32 v[62:63], v[80:81], v[62:63]
	v_mul_f32_e32 v2, 0xbfb8aa3b, v2
	v_mul_f32_e32 v60, 0xbfb8aa3b, v75
	v_mul_f32_e32 v46, v46, v56
	v_pk_fma_f32 v[62:63], v[84:85], v[76:77], v[62:63]
	v_and_b32_e32 v76, 0xffff0000, v58
	v_lshlrev_b32_e32 v77, 16, v59
	v_and_b32_e32 v78, 0xffff0000, v59
	v_lshlrev_b32_e32 v58, 16, v61
	v_and_b32_e32 v59, 0xffff0000, v61
	v_exp_f32_e32 v2, v2
	v_exp_f32_e32 v60, v60
	s_mov_b32 s100, 0x9f5d000
	v_lshl_add_u64 v[22:23], v[20:21], 0, s[100:101]
	global_load_dwordx4 v[36:39], v[22:23], off offset:1024
	v_exp_f32_e32 v61, v46
	v_mul_f32_e32 v46, 0xbfb8aa3b, v72
	v_fmamk_f32 v47, v47, 0xbdd2d3e7, v93
	v_pk_mul_f32 v[70:71], v[0:1], v[44:45] op_sel_hi:[0,1]
	v_pk_mul_f32 v[44:45], v[58:59], v[58:59]
	v_exp_f32_e32 v75, v46
	v_mul_f32_e32 v46, 0xbfb8aa3b, v76
	v_mul_f32_e32 v47, v47, v57
	v_exp_f32_e32 v46, v46
	v_exp_f32_e32 v47, v47
	v_mul_f32_e32 v72, 0xbfb8aa3b, v73
	v_fmamk_f32 v44, v44, 0xbdd2d3e7, v93
	v_exp_f32_e32 v76, v72
	v_mul_f32_e32 v72, 0xbfb8aa3b, v77
	v_mul_f32_e32 v44, v44, v58
	v_exp_f32_e32 v72, v72
	v_exp_f32_e32 v73, v44
	v_mul_f32_e32 v44, 0xbfb8aa3b, v74
	v_fmamk_f32 v45, v45, 0xbdd2d3e7, v93
	v_add_f32_e32 v2, 1.0, v2
	v_pk_add_f32 v[60:61], v[60:61], 1.0 op_sel_hi:[1,0]
	v_exp_f32_e32 v77, v44
	v_mul_f32_e32 v44, 0xbfb8aa3b, v78
	v_mul_f32_e32 v45, v45, v59
	v_rcp_f32_e32 v74, v2
	v_mul_f32_e32 v2, v60, v61
	v_exp_f32_e32 v44, v44
	v_exp_f32_e32 v45, v45
	v_rcp_f32_e32 v60, v2
	v_add_f32_e32 v2, 1.0, v75
	v_pk_add_f32 v[46:47], v[46:47], 1.0 op_sel_hi:[1,0]
	v_rcp_f32_e32 v75, v2
	v_mul_f32_e32 v2, v46, v47
	v_rcp_f32_e32 v61, v2
	v_add_f32_e32 v2, 1.0, v76
	v_pk_add_f32 v[46:47], v[72:73], 1.0 op_sel_hi:[1,0]
	v_cvt_pk_bf16_f32 v62, v62, v63
	v_cvt_pk_bf16_f32 v63, v64, v65
	v_rcp_f32_e32 v76, v2
	v_mul_f32_e32 v2, v46, v47
	v_mov_b64_e32 v[240:241], v[62:63]
	s_nop 1
	v_permlane16_swap_b32_e32 v238, v240
	v_permlane16_swap_b32_e32 v239, v241
	global_store_dwordx4 v[158:159], v[238:241], off
	ds_read_b128 v[62:65], v1 offset:128
	v_rcp_f32_e32 v72, v2
	v_add_f32_e32 v2, 1.0, v77
	v_pk_add_f32 v[44:45], v[44:45], 1.0 op_sel_hi:[1,0]
	v_rcp_f32_e32 v77, v2
	v_mul_f32_e32 v2, v44, v45
	v_rcp_f32_e32 v73, v2
	ds_read_b128 v[44:47], v1 offset:192
	s_waitcnt lgkmcnt(1)
	v_pk_mul_f32 v[58:59], v[64:65], v[58:59]
	v_pk_mul_f32 v[56:57], v[62:63], v[56:57]
	v_pk_mul_f32 v[58:59], v[72:73], v[58:59]
	v_pk_mul_f32 v[56:57], v[60:61], v[56:57]
	v_pk_fma_f32 v[58:59], v[76:77], v[66:67], v[58:59]
	v_pk_fma_f32 v[56:57], v[74:75], v[70:71], v[56:57]
	v_pk_mul_f32 v[42:43], v[0:1], v[42:43] op_sel_hi:[0,1]
	v_pk_mul_f32 v[0:1], v[0:1], v[40:41] op_sel_hi:[0,1]
	v_lshlrev_b32_e32 v40, 16, v54
	s_mov_b32 s100, s66
	v_lshl_add_u64 v[32:33], v[20:21], 0, s[100:101]
	global_load_dwordx4 v[32:35], v[32:33], off
	v_and_b32_e32 v41, 0xffff0000, v54
	v_cvt_pk_bf16_f32 v56, v56, v57
	v_cvt_pk_bf16_f32 v57, v58, v59
	v_lshlrev_b32_e32 v2, 16, v48
	v_and_b32_e32 v58, 0xffff0000, v48
	v_lshlrev_b32_e32 v59, 16, v49
	v_and_b32_e32 v60, 0xffff0000, v49
	v_lshlrev_b32_e32 v48, 16, v55
	v_and_b32_e32 v49, 0xffff0000, v55
	v_pk_mul_f32 v[54:55], v[40:41], v[40:41]
	v_mov_b64_e32 v[242:243], v[56:57]
	v_lshlrev_b32_e32 v56, 16, v50
	v_fmamk_f32 v54, v54, 0xbdd2d3e7, v93
	v_mul_f32_e32 v2, 0xbfb8aa3b, v2
	v_mul_f32_e32 v56, 0xbfb8aa3b, v56
	v_mul_f32_e32 v54, v54, v40
	v_and_b32_e32 v61, 0xffff0000, v50
	v_exp_f32_e32 v2, v2
	v_exp_f32_e32 v56, v56
	v_exp_f32_e32 v57, v54
	v_mul_f32_e32 v54, 0xbfb8aa3b, v58
	v_fmamk_f32 v55, v55, 0xbdd2d3e7, v93
	v_lshlrev_b32_e32 v62, 16, v51
	v_and_b32_e32 v63, 0xffff0000, v51
	v_pk_mul_f32 v[50:51], v[48:49], v[48:49]
	v_exp_f32_e32 v64, v54
	v_mul_f32_e32 v54, 0xbfb8aa3b, v61
	v_mul_f32_e32 v55, v55, v41
	v_exp_f32_e32 v54, v54
	v_exp_f32_e32 v55, v55
	v_mul_f32_e32 v58, 0xbfb8aa3b, v59
	v_fmamk_f32 v50, v50, 0xbdd2d3e7, v93
	v_exp_f32_e32 v65, v58
	v_mul_f32_e32 v58, 0xbfb8aa3b, v62
	v_mul_f32_e32 v50, v50, v48
	v_exp_f32_e32 v58, v58
	v_exp_f32_e32 v59, v50
	v_mul_f32_e32 v50, 0xbfb8aa3b, v60
	v_fmamk_f32 v51, v51, 0xbdd2d3e7, v93
	v_add_f32_e32 v2, 1.0, v2
	v_pk_add_f32 v[56:57], v[56:57], 1.0 op_sel_hi:[1,0]
	v_exp_f32_e32 v62, v50
	v_mul_f32_e32 v50, 0xbfb8aa3b, v63
	v_mul_f32_e32 v51, v51, v49
	v_rcp_f32_e32 v60, v2
	s_mov_b32 s100, 0x9f62000
	v_lshl_add_u64 v[20:21], v[20:21], 0, s[100:101]
	global_load_dwordx4 v[20:23], v[20:21], off offset:3072
	v_mul_f32_e32 v2, v56, v57
	v_exp_f32_e32 v50, v50
	v_exp_f32_e32 v51, v51
	v_rcp_f32_e32 v56, v2
	v_add_f32_e32 v2, 1.0, v64
	v_pk_add_f32 v[54:55], v[54:55], 1.0 op_sel_hi:[1,0]
	v_rcp_f32_e32 v61, v2
	v_mul_f32_e32 v2, v54, v55
	v_rcp_f32_e32 v57, v2
	v_add_f32_e32 v2, 1.0, v65
	v_pk_add_f32 v[58:59], v[58:59], 1.0 op_sel_hi:[1,0]
	v_rcp_f32_e32 v54, v2
	v_mul_f32_e32 v2, v58, v59
	v_rcp_f32_e32 v58, v2
	v_add_f32_e32 v2, 1.0, v62
	v_pk_add_f32 v[50:51], v[50:51], 1.0 op_sel_hi:[1,0]
	v_rcp_f32_e32 v55, v2
	v_mul_f32_e32 v2, v50, v51
	v_rcp_f32_e32 v59, v2
	s_waitcnt lgkmcnt(0)
	v_pk_mul_f32 v[46:47], v[46:47], v[48:49]
	v_pk_mul_f32 v[40:41], v[44:45], v[40:41]
	s_addk_i32 s38, 0x80
	v_pk_mul_f32 v[40:41], v[56:57], v[40:41]
	v_pk_mul_f32 v[44:45], v[58:59], v[46:47]
	v_pk_fma_f32 v[0:1], v[60:61], v[0:1], v[40:41]
	v_pk_fma_f32 v[42:43], v[54:55], v[42:43], v[44:45]
	v_cvt_pk_bf16_f32 v0, v0, v1
	v_cvt_pk_bf16_f32 v1, v42, v43
	v_mov_b64_e32 v[244:245], v[0:1]
	s_nop 1
	v_permlane16_swap_b32_e32 v242, v244
	v_permlane16_swap_b32_e32 v243, v245
	global_store_dwordx4 v[158:159], v[242:245], off offset:64
	s_waitcnt lgkmcnt(0)
	s_barrier
	s_add_u32 s54, s54, 0x160000
	s_addc_u32 s55, s55, 0
	s_cmp_eq_u32 s54, 0x1600000
	s_cbranch_scc1 .LBB0_281
